# ATT_B: precomputed per-lane LDS-DMA offsets + SGPR exec masks in tile loop; static s_setprio 1 for waves 4-7 during ATT_B
# speedup vs baseline: 1.0062x; 1.0062x over previous
; template <int DQK, bool WIN>
; __device__ __forceinline__ void attn_phase(const Params& P, unsigned char* ws, LAS unsigned char* lds, int layer_j, bool with_ctx, int tid, int lane, int wave) {
;     ...
;     const int G_ = gridDim.x, bx_ = blockIdx.x, vcu = (G_ % 8 == 0) ? (bx_ % 8) * (G_ / 8) + bx_ / 8 : bx_;
;     for (int u = vcu; u < nunits; u += G_) {
.LBB0_179:
	s_and_b64 vcc, exec, s[0:1]
	s_cbranch_vccz .LBB0_320
	v_readlane_b32 s0, v253, 40
	s_cmp_gt_i32 s0, 9
	s_mov_b64 s[0:1], -1
	s_cbranch_scc0 .LBB0_309
	v_readlane_b32 s0, v253, 40
	s_cmp_eq_u32 s0, 10
	s_mov_b64 s[2:3], -1
	s_cbranch_scc0 .LBB0_308
	v_readlane_b32 s0, v252, 44
	s_mov_b32 s86, s19
	s_cmp_ge_i32 s0, s44
	s_cbranch_scc1 .LBB0_318
	s_add_u32 s10, s20, 0xdb00000
	v_and_b32_e32 v2, 48, v221
	v_mov_b32_e32 v3, v1
	s_addc_u32 s12, s21, 0
	v_lshl_add_u64 v[2:3], s[20:21], 0, v[2:3]
	s_mov_b64 s[0:1], 0x14100000
	s_add_u32 s2, s20, 0x1a700000
	v_lshrrev_b32_e32 v13, 4, v221
	v_lshl_add_u64 v[200:201], v[2:3], 0, s[0:1]
	v_readlane_b32 s0, v253, 51
	s_addc_u32 s3, s21, 0
	v_lshlrev_b32_e32 v0, 3, v13
	s_lshl_b32 s14, s0, 11
	s_add_i32 s19, s14, 0
	v_lshl_add_u64 v[2:3], s[20:21], 0, v[0:1]
	s_mov_b64 s[0:1], 0x6400000
	v_lshlrev_b32_e32 v0, 2, v221
	v_and_b32_e32 v198, 15, v196
	s_and_b32 s13, s86, 0xffffffc0
	v_mov_b32_e32 v199, v1
	s_or_b32 s22, s14, 0x400
	v_cmp_eq_u32_e64 s[38:39], 0, v196
	v_lshl_add_u64 v[202:203], v[2:3], 0, s[0:1]
	v_cmp_eq_u32_e64 s[40:41], 0, v221
	v_xor_b32_e32 v197, 64, v0
	v_xor_b32_e32 v206, 0x80, v0
	s_add_i32 s23, s19, 0x4400
	s_add_i32 s45, s19, 0xc400
	v_lshrrev_b32_e32 v0, 4, v221
	v_and_b32_e32 v2, 15, v221
	s_lshr_b32 s0, s14, 11
	s_lshl_b32 s1, s0, 3
	v_add_u32_e32 v3, s1, v0
	s_and_b32 s1, s0, 3
	s_lshl_b32 s1, s1, 2
	v_or_b32_e32 v238, s1, v0
	v_xor_b32_e32 v238, v238, v2
	v_cmp_gt_u32_e32 vcc, 12, v238
	s_mov_b64 s[98:99], vcc
	v_lshlrev_b32_e32 v238, 4, v238
	s_movk_i32 s1, 0xc00
	v_mad_u32_u24 v238, v3, s1, v238
	v_add_u32_e32 v241, 0x2c00, v238
	s_and_b32 s1, s0, 1
	s_lshl_b32 s1, s1, 3
	v_or_b32_e32 v239, s1, v0
	v_xor_b32_e32 v239, v239, v2
	v_cmp_gt_u32_e32 vcc, 8, v239
	s_mov_b64 s[100:101], vcc
	v_xor_b32_e32 v240, 4, v239
	v_lshlrev_b32_e32 v239, 4, v239
	v_lshlrev_b32_e32 v240, 4, v240
	s_movk_i32 s1, 0x2200
	v_mad_u32_u24 v239, v3, s1, v239
	v_add_u32_e32 v3, 4, v3
	v_mad_u32_u24 v240, v3, s1, v240
	v_add_u32_e32 v240, 0xfffffc00, v240
	s_cmp_lt_u32 s0, 4
	s_cbranch_scc1 .Lmy_attb_noprio
	s_setprio 1
.Lmy_attb_noprio:
	v_readlane_b32 s58, v252, 44
	s_branch .LBB0_186

; template <int DQK, bool WIN, bool SAFE>
; __device__ __forceinline__ bool attn_unit(const Params& P, unsigned char* ws, LAS unsigned char* lds, int layer_j, int u, int tid, int lane, int wave) {
;     ...
;             if (t2 + 2 < nt) { AT_DMA(t2 + 2); AT_DMA(t2 + 3); }
.LBB0_218:
	s_cmp_ge_u32 s66, s59
	s_cselect_b64 s[56:57], -1, 0
	s_and_b64 vcc, exec, s[56:57]
	s_cbranch_vccnz .LBB0_237
	s_mov_b64 s[28:29], exec
	s_add_i32 s43, s52, s65
	s_add_i32 s42, s43, 0xffffffc0
	s_cmp_eq_u32 s54, 0
	s_cselect_b32 s42, s46, s42
	s_cselect_b32 s43, s48, s43
	s_mul_i32 s42, s42, 0xc00
	s_mul_i32 s43, s43, 0xc00
	s_add_u32 s30, s50, s42
	s_addc_u32 s31, s51, 0
	s_add_u32 s84, s50, s43
	s_addc_u32 s85, s51, 0
	s_add_u32 s8, s62, s54
	s_addc_u32 s9, s63, s55
	s_add_u32 s8, s8, 0x1a700100
	s_addc_u32 s9, s9, 0
	s_add_i32 s42, s64, 0xffff8000
	s_and_b32 s42, s42, 0x10000
	s_add_i32 s42, s42, s19
	s_and_b32 s43, s64, 0x18000
	s_add_i32 s43, s43, s19
	s_mov_b32 m0, s42
	s_mov_b64 exec, s[98:99]
	global_load_lds_dwordx4 v238, s[30:31]
	global_load_lds_dwordx4 v241, s[30:31] offset:1024
	s_add_i32 m0, s42, 0x4000
	s_mov_b64 exec, s[100:101]
	global_load_lds_dwordx4 v239, s[8:9]
	global_load_lds_dwordx4 v240, s[8:9] offset:1024
	s_add_u32 s8, s8, 0x80
	s_addc_u32 s9, s9, 0
	s_mov_b32 m0, s43
	s_mov_b64 exec, s[98:99]
	global_load_lds_dwordx4 v238, s[84:85]
	global_load_lds_dwordx4 v241, s[84:85] offset:1024
	s_add_i32 m0, s43, 0x4000
	s_mov_b64 exec, s[100:101]
	global_load_lds_dwordx4 v239, s[8:9]
	global_load_lds_dwordx4 v240, s[8:9] offset:1024
	s_mov_b64 exec, s[28:29]
	v_cndmask_b32_e64 v0, 0, 1, s[26:27]
	v_cmp_ne_u32_e64 s[42:43], 1, v0
	s_andn2_b64 vcc, exec, s[26:27]
	s_cbranch_vccz .LBB0_238

; template <int DQK, bool WIN>
; __device__ __forceinline__ void attn_phase(const Params& P, unsigned char* ws, LAS unsigned char* lds, int layer_j, bool with_ctx, int tid, int lane, int wave) {
;     ...
;     __syncthreads();
.LBB0_318:
	s_setprio 0
	s_waitcnt vmcnt(0) lgkmcnt(0)
	s_barrier
	s_mov_b64 s[2:3], 0
	s_mov_b32 s19, s86
	s_branch .LBB0_320

; __global__ void __launch_bounds__(NTHR, 2) fwd_megakernel(Params P) {
	.amdhsa_kernel _Z14fwd_megakernel6Params
		.amdhsa_group_segment_fixed_size 0
		.amdhsa_private_segment_fixed_size 0
		.amdhsa_kernarg_size 464
		.amdhsa_user_sgpr_count 2
		.amdhsa_user_sgpr_dispatch_ptr 0
		.amdhsa_user_sgpr_queue_ptr 0
		.amdhsa_user_sgpr_kernarg_segment_ptr 1
		.amdhsa_user_sgpr_dispatch_id 0
		.amdhsa_user_sgpr_kernarg_preload_length 0
		.amdhsa_user_sgpr_kernarg_preload_offset 0
		.amdhsa_user_sgpr_private_segment_size 0
		.amdhsa_uses_dynamic_stack 0
		.amdhsa_enable_private_segment 0
		.amdhsa_system_sgpr_workgroup_id_x 1
		.amdhsa_system_sgpr_workgroup_id_y 0
		.amdhsa_system_sgpr_workgroup_id_z 0
		.amdhsa_system_sgpr_workgroup_info 0
		.amdhsa_system_vgpr_workitem_id 2
		.amdhsa_next_free_vgpr 254
		.amdhsa_next_free_sgpr 102
		.amdhsa_accum_offset 256
		.amdhsa_reserve_vcc 1
		.amdhsa_float_round_mode_32 0
		.amdhsa_float_round_mode_16_64 0
		.amdhsa_float_denorm_mode_32 3
		.amdhsa_float_denorm_mode_16_64 3
		.amdhsa_dx10_clamp 1
		.amdhsa_ieee_mode 1
		.amdhsa_fp16_overflow 0
		.amdhsa_tg_split 0
		.amdhsa_exception_fp_ieee_invalid_op 0
		.amdhsa_exception_fp_denorm_src 0
		.amdhsa_exception_fp_ieee_div_zero 0
		.amdhsa_exception_fp_ieee_overflow 0
		.amdhsa_exception_fp_ieee_underflow 0
		.amdhsa_exception_fp_ieee_inexact 0
		.amdhsa_exception_int_div_zero 0
	.end_amdhsa_kernel

; __global__ void __launch_bounds__(NTHR, 2) fwd_megakernel(Params P) {
amdhsa.kernels:
  - .agpr_count:     0
    .args:
      - .offset:         0
        .size:           208
        .value_kind:     by_value
      - .offset:         208
        .size:           4
        .value_kind:     hidden_block_count_x
      - .offset:         212
        .size:           4
        .value_kind:     hidden_block_count_y
      - .offset:         216
        .size:           4
        .value_kind:     hidden_block_count_z
      - .offset:         220
        .size:           2
        .value_kind:     hidden_group_size_x
      - .offset:         222
        .size:           2
        .value_kind:     hidden_group_size_y
      - .offset:         224
        .size:           2
        .value_kind:     hidden_group_size_z
      - .offset:         226
        .size:           2
        .value_kind:     hidden_remainder_x
      - .offset:         228
        .size:           2
        .value_kind:     hidden_remainder_y
      - .offset:         230
        .size:           2
        .value_kind:     hidden_remainder_z
      - .offset:         248
        .size:           8
        .value_kind:     hidden_global_offset_x
      - .offset:         256
        .size:           8
        .value_kind:     hidden_global_offset_y
      - .offset:         264
        .size:           8
        .value_kind:     hidden_global_offset_z
      - .offset:         272
        .size:           2
        .value_kind:     hidden_grid_dims
      - .offset:         296
        .size:           8
        .value_kind:     hidden_multigrid_sync_arg
      - .offset:         328
        .size:           4
        .value_kind:     hidden_dynamic_lds_size
    .group_segment_fixed_size: 0
    .kernarg_segment_align: 8
    .kernarg_segment_size: 464
    .language:       OpenCL C
    .language_version:
      - 2
      - 0
    .max_flat_workgroup_size: 512
    .name:           _Z14fwd_megakernel6Params
    .private_segment_fixed_size: 0
    .sgpr_count:     108
    .sgpr_spill_count: 347
    .symbol:         _Z14fwd_megakernel6Params.kd
    .uniform_work_group_size: 1
    .uses_dynamic_stack: false
    .vgpr_count:     254
    .vgpr_spill_count: 0
    .wavefront_size: 64
